# gate-up GEMM K-loop: four of the six LDS-DMA pieces of each second super-phase issued under its MFMA block (counted waits adjusted); attention fast path with in-path tile DMA
# speedup vs baseline: 1.0126x; 1.0052x over previous
.LBB0_235:
	s_add_i32 s23, s22, 2
	s_add_u32 s60, s58, 0xfff80080
	s_addc_u32 s61, s59, -1
	s_add_i32 s64, 0, 0x10000
	s_cmp_eq_u32 s72, s22
	s_cselect_b32 s63, s21, s61
	s_cselect_b32 s62, s43, s60
	v_add_u32_e32 v152, s64, v156
	s_cselect_b32 s61, s45, s74
	s_cselect_b32 s60, s47, s73
	s_add_i32 s22, 0, 0x14000
	ds_read_b128 v[144:147], v152
	ds_read_b128 v[148:151], v152 offset:1024
	ds_read_b128 v[164:167], v152 offset:2048
	ds_read_b128 v[168:171], v152 offset:3072
	v_add_u32_e32 v152, s22, v156
	ds_read_b128 v[172:175], v152
	ds_read_b128 v[176:179], v152 offset:1024
	ds_read_b128 v[180:183], v152 offset:2048
	ds_read_b128 v[184:187], v152 offset:3072
	v_add_u32_e32 v163, 0, v155
	v_lshl_add_u64 v[152:153], s[58:59], 0, v[140:141]
	s_add_i32 m0, s11, 0xc000
	ds_read_b128 v[188:191], v163
	ds_read_b128 v[192:195], v163 offset:1024
	ds_read_b128 v[200:203], v163 offset:2048
	ds_read_b128 v[204:207], v163 offset:3072
	ds_read_b128 v[208:211], v163 offset:4096
	ds_read_b128 v[212:215], v163 offset:5120
	ds_read_b128 v[216:219], v163 offset:6144
	ds_read_b128 v[220:223], v163 offset:7168
	global_load_lds_dwordx4 v[152:153], off
	v_lshl_add_u64 v[152:153], s[58:59], 0, v[142:143]
	s_add_i32 m0, s11, 0xe000
	s_nop 0
	global_load_lds_dwordx4 v[152:153], off
	s_waitcnt vmcnt(8)
	s_waitcnt lgkmcnt(0)
	s_barrier
	s_setprio 1
	s_waitcnt lgkmcnt(0)
	v_mfma_f32_16x16x32_bf16 v[128:131], v[144:147], v[188:191], v[128:131]
	v_mfma_f32_16x16x32_bf16 v[124:127], v[164:167], v[188:191], v[124:127]
	v_mfma_f32_16x16x32_bf16 v[112:115], v[144:147], v[200:203], v[112:115]
	v_mfma_f32_16x16x32_bf16 v[108:111], v[164:167], v[200:203], v[108:111]
	v_mfma_f32_16x16x32_bf16 v[96:99], v[144:147], v[208:211], v[96:99]
	v_mfma_f32_16x16x32_bf16 v[92:95], v[164:167], v[208:211], v[92:95]
	v_mfma_f32_16x16x32_bf16 v[80:83], v[144:147], v[216:219], v[80:83]
	v_mfma_f32_16x16x32_bf16 v[76:79], v[164:167], v[216:219], v[76:79]
	v_mfma_f32_16x16x32_bf16 v[128:131], v[148:151], v[192:195], v[128:131]
	v_mfma_f32_16x16x32_bf16 v[124:127], v[168:171], v[192:195], v[124:127]
	v_mfma_f32_16x16x32_bf16 v[112:115], v[148:151], v[204:207], v[112:115]
	v_mfma_f32_16x16x32_bf16 v[108:111], v[168:171], v[204:207], v[108:111]
	v_mfma_f32_16x16x32_bf16 v[96:99], v[148:151], v[212:215], v[96:99]
	v_mfma_f32_16x16x32_bf16 v[92:95], v[168:171], v[212:215], v[92:95]
	v_mfma_f32_16x16x32_bf16 v[80:83], v[148:151], v[220:223], v[80:83]
	v_mfma_f32_16x16x32_bf16 v[76:79], v[168:171], v[220:223], v[76:79]
	s_setprio 0
	s_setprio 1
	v_mfma_f32_16x16x32_bf16 v[120:123], v[172:175], v[188:191], v[120:123]
	v_mfma_f32_16x16x32_bf16 v[116:119], v[180:183], v[188:191], v[116:119]
	v_mfma_f32_16x16x32_bf16 v[104:107], v[172:175], v[200:203], v[104:107]
	v_mfma_f32_16x16x32_bf16 v[100:103], v[180:183], v[200:203], v[100:103]
	v_mfma_f32_16x16x32_bf16 v[88:91], v[172:175], v[208:211], v[88:91]
	v_mfma_f32_16x16x32_bf16 v[84:87], v[180:183], v[208:211], v[84:87]
	v_mfma_f32_16x16x32_bf16 v[72:75], v[172:175], v[216:219], v[72:75]
	v_mfma_f32_16x16x32_bf16 v[68:71], v[180:183], v[216:219], v[68:71]
	v_mfma_f32_16x16x32_bf16 v[120:123], v[176:179], v[192:195], v[120:123]
	v_mfma_f32_16x16x32_bf16 v[116:119], v[184:187], v[192:195], v[116:119]
	v_mfma_f32_16x16x32_bf16 v[104:107], v[176:179], v[204:207], v[104:107]
	v_mfma_f32_16x16x32_bf16 v[100:103], v[184:187], v[204:207], v[100:103]
	v_mfma_f32_16x16x32_bf16 v[88:91], v[176:179], v[212:215], v[88:91]
	v_mfma_f32_16x16x32_bf16 v[84:87], v[184:187], v[212:215], v[84:87]
	v_mfma_f32_16x16x32_bf16 v[72:75], v[176:179], v[220:223], v[72:75]
	v_mfma_f32_16x16x32_bf16 v[68:71], v[184:187], v[220:223], v[68:71]
	s_setprio 0
	s_barrier
	s_add_i32 s64, s64, s6
	v_lshl_add_u64 v[152:153], s[60:61], 0, v[66:67]
	s_mov_b32 m0, s64
	ds_read_b128 v[188:191], v163 offset:16384
	ds_read_b128 v[192:195], v163 offset:17408
	ds_read_b128 v[200:203], v163 offset:18432
	ds_read_b128 v[204:207], v163 offset:19456
	ds_read_b128 v[208:211], v163 offset:20480
	ds_read_b128 v[212:215], v163 offset:21504
	ds_read_b128 v[216:219], v163 offset:22528
	ds_read_b128 v[220:223], v163 offset:23552
	global_load_lds_dwordx4 v[152:153], off
	s_add_i32 m0, s64, 0x2000
	s_add_u32 s64, s60, 0x80000
	v_lshl_add_u64 v[230:231], s[60:61], 0, v[136:137]
	s_addc_u32 s65, s61, 0
	s_add_i32 s22, s22, s6
	global_load_lds_dwordx4 v[230:231], off
	s_waitcnt vmcnt(4)
	s_waitcnt lgkmcnt(0)
	s_barrier
	s_setprio 1
	s_waitcnt lgkmcnt(0)
	v_mfma_f32_16x16x32_bf16 v[62:65], v[144:147], v[188:191], v[62:65]
	v_mfma_f32_16x16x32_bf16 v[58:61], v[164:167], v[188:191], v[58:61]
	v_mfma_f32_16x16x32_bf16 v[46:49], v[144:147], v[200:203], v[46:49]
	v_mfma_f32_16x16x32_bf16 v[42:45], v[164:167], v[200:203], v[42:45]
	v_mfma_f32_16x16x32_bf16 v[30:33], v[144:147], v[208:211], v[30:33]
	v_mfma_f32_16x16x32_bf16 v[26:29], v[164:167], v[208:211], v[26:29]
	v_lshl_add_u64 v[232:233], s[64:65], 0, v[66:67]
	s_mov_b32 m0, s22
	v_lshl_add_u64 v[234:235], s[62:63], 0, v[134:135]
	global_load_lds_dwordx4 v[232:233], off
	v_mfma_f32_16x16x32_bf16 v[14:17], v[144:147], v[216:219], v[14:17]
	v_mfma_f32_16x16x32_bf16 v[10:13], v[164:167], v[216:219], v[10:13]
	v_mfma_f32_16x16x32_bf16 v[62:65], v[148:151], v[192:195], v[62:65]
	v_mfma_f32_16x16x32_bf16 v[58:61], v[168:171], v[192:195], v[58:61]
	v_mfma_f32_16x16x32_bf16 v[46:49], v[148:151], v[204:207], v[46:49]
	v_mfma_f32_16x16x32_bf16 v[42:45], v[168:171], v[204:207], v[42:45]
	v_lshl_add_u64 v[232:233], s[64:65], 0, v[136:137]
	s_add_i32 m0, s22, 0x2000
	s_nop 0
	global_load_lds_dwordx4 v[232:233], off
	v_mfma_f32_16x16x32_bf16 v[30:33], v[148:151], v[212:215], v[30:33]
	v_mfma_f32_16x16x32_bf16 v[26:29], v[168:171], v[212:215], v[26:29]
	v_mfma_f32_16x16x32_bf16 v[14:17], v[148:151], v[220:223], v[14:17]
	v_mfma_f32_16x16x32_bf16 v[10:13], v[168:171], v[220:223], v[10:13]
	s_setprio 0
	s_setprio 1
	v_mfma_f32_16x16x32_bf16 v[54:57], v[172:175], v[188:191], v[54:57]
	v_mfma_f32_16x16x32_bf16 v[50:53], v[180:183], v[188:191], v[50:53]
	v_lshl_add_u64 v[232:233], s[62:63], 0, v[132:133]
	s_mov_b32 m0, s11
	s_nop 0
	global_load_lds_dwordx4 v[232:233], off
	v_mfma_f32_16x16x32_bf16 v[38:41], v[172:175], v[200:203], v[38:41]
	v_mfma_f32_16x16x32_bf16 v[34:37], v[180:183], v[200:203], v[34:37]
	v_mfma_f32_16x16x32_bf16 v[22:25], v[172:175], v[208:211], v[22:25]
	v_mfma_f32_16x16x32_bf16 v[18:21], v[180:183], v[208:211], v[18:21]
	v_mfma_f32_16x16x32_bf16 v[6:9], v[172:175], v[216:219], v[6:9]
	v_mfma_f32_16x16x32_bf16 v[2:5], v[180:183], v[216:219], v[2:5]
	s_mov_b32 m0, s12
	s_nop 0
	global_load_lds_dwordx4 v[234:235], off
	v_mfma_f32_16x16x32_bf16 v[54:57], v[176:179], v[192:195], v[54:57]
	v_mfma_f32_16x16x32_bf16 v[50:53], v[184:187], v[192:195], v[50:53]
	v_mfma_f32_16x16x32_bf16 v[38:41], v[176:179], v[204:207], v[38:41]
	v_mfma_f32_16x16x32_bf16 v[34:37], v[184:187], v[204:207], v[34:37]
	v_mfma_f32_16x16x32_bf16 v[22:25], v[176:179], v[212:215], v[22:25]
	v_mfma_f32_16x16x32_bf16 v[18:21], v[184:187], v[212:215], v[18:21]
	v_mfma_f32_16x16x32_bf16 v[6:9], v[176:179], v[220:223], v[6:9]
	v_mfma_f32_16x16x32_bf16 v[2:5], v[184:187], v[220:223], v[2:5]
	s_setprio 0
	s_barrier
	s_add_i32 s22, 0, 0x18000
	s_add_i32 s64, 0, 0x1c000
	v_add_u32_e32 v168, s22, v156
	v_add_u32_e32 v184, s64, v156
	ds_read_b128 v[144:147], v168
	ds_read_b128 v[148:151], v168 offset:1024
	ds_read_b128 v[164:167], v168 offset:2048
	ds_read_b128 v[168:171], v168 offset:3072
	ds_read_b128 v[172:175], v184
	ds_read_b128 v[176:179], v184 offset:1024
	ds_read_b128 v[180:183], v184 offset:2048
	ds_read_b128 v[184:187], v184 offset:3072
	s_add_u32 s62, s62, 0x80000
	s_addc_u32 s63, s63, 0
	s_mov_b32 m0, s13
	v_lshl_add_u64 v[236:237], s[62:63], 0, v[132:133]
	ds_read_b128 v[188:191], v163 offset:32768
	ds_read_b128 v[192:195], v163 offset:33792
	ds_read_b128 v[200:203], v163 offset:34816
	ds_read_b128 v[204:207], v163 offset:35840
	ds_read_b128 v[208:211], v163 offset:36864
	ds_read_b128 v[212:215], v163 offset:37888
	ds_read_b128 v[216:219], v163 offset:38912
	ds_read_b128 v[220:223], v163 offset:39936
	global_load_lds_dwordx4 v[236:237], off
	v_lshl_add_u64 v[236:237], s[62:63], 0, v[134:135]
	s_mov_b32 m0, s14
	s_nop 0
	global_load_lds_dwordx4 v[236:237], off
	s_waitcnt vmcnt(8)
	s_waitcnt lgkmcnt(0)
	s_barrier
	s_setprio 1
	s_waitcnt lgkmcnt(0)
	v_mfma_f32_16x16x32_bf16 v[128:131], v[144:147], v[188:191], v[128:131]
	v_mfma_f32_16x16x32_bf16 v[124:127], v[164:167], v[188:191], v[124:127]
	v_mfma_f32_16x16x32_bf16 v[112:115], v[144:147], v[200:203], v[112:115]
	v_mfma_f32_16x16x32_bf16 v[108:111], v[164:167], v[200:203], v[108:111]
	v_mfma_f32_16x16x32_bf16 v[96:99], v[144:147], v[208:211], v[96:99]
	v_mfma_f32_16x16x32_bf16 v[92:95], v[164:167], v[208:211], v[92:95]
	v_mfma_f32_16x16x32_bf16 v[80:83], v[144:147], v[216:219], v[80:83]
	v_mfma_f32_16x16x32_bf16 v[76:79], v[164:167], v[216:219], v[76:79]
	v_mfma_f32_16x16x32_bf16 v[128:131], v[148:151], v[192:195], v[128:131]
	v_mfma_f32_16x16x32_bf16 v[124:127], v[168:171], v[192:195], v[124:127]
	v_mfma_f32_16x16x32_bf16 v[112:115], v[148:151], v[204:207], v[112:115]
	v_mfma_f32_16x16x32_bf16 v[108:111], v[168:171], v[204:207], v[108:111]
	v_mfma_f32_16x16x32_bf16 v[96:99], v[148:151], v[212:215], v[96:99]
	v_mfma_f32_16x16x32_bf16 v[92:95], v[168:171], v[212:215], v[92:95]
	v_mfma_f32_16x16x32_bf16 v[80:83], v[148:151], v[220:223], v[80:83]
	v_mfma_f32_16x16x32_bf16 v[76:79], v[168:171], v[220:223], v[76:79]
	s_setprio 0
	s_setprio 1
	v_mfma_f32_16x16x32_bf16 v[120:123], v[172:175], v[188:191], v[120:123]
	v_mfma_f32_16x16x32_bf16 v[116:119], v[180:183], v[188:191], v[116:119]
	v_mfma_f32_16x16x32_bf16 v[104:107], v[172:175], v[200:203], v[104:107]
	v_mfma_f32_16x16x32_bf16 v[100:103], v[180:183], v[200:203], v[100:103]
	v_mfma_f32_16x16x32_bf16 v[88:91], v[172:175], v[208:211], v[88:91]
	v_mfma_f32_16x16x32_bf16 v[84:87], v[180:183], v[208:211], v[84:87]
	v_mfma_f32_16x16x32_bf16 v[72:75], v[172:175], v[216:219], v[72:75]
	v_mfma_f32_16x16x32_bf16 v[68:71], v[180:183], v[216:219], v[68:71]
	v_mfma_f32_16x16x32_bf16 v[120:123], v[176:179], v[192:195], v[120:123]
	v_mfma_f32_16x16x32_bf16 v[116:119], v[184:187], v[192:195], v[116:119]
	v_mfma_f32_16x16x32_bf16 v[104:107], v[176:179], v[204:207], v[104:107]
	v_mfma_f32_16x16x32_bf16 v[100:103], v[184:187], v[204:207], v[100:103]
	v_mfma_f32_16x16x32_bf16 v[88:91], v[176:179], v[212:215], v[88:91]
	v_mfma_f32_16x16x32_bf16 v[84:87], v[184:187], v[212:215], v[84:87]
	v_mfma_f32_16x16x32_bf16 v[72:75], v[176:179], v[220:223], v[72:75]
	v_mfma_f32_16x16x32_bf16 v[68:71], v[184:187], v[220:223], v[68:71]
	s_setprio 0
	s_barrier
	s_add_i32 s22, s22, s6
	v_lshl_add_u64 v[152:153], v[152:153], 0, s[30:31]
	s_mov_b32 m0, s22
	ds_read_b128 v[188:191], v163 offset:49152
	ds_read_b128 v[192:195], v163 offset:50176
	ds_read_b128 v[200:203], v163 offset:51200
	ds_read_b128 v[204:207], v163 offset:52224
	ds_read_b128 v[208:211], v163 offset:53248
	ds_read_b128 v[212:215], v163 offset:54272
	ds_read_b128 v[216:219], v163 offset:55296
	ds_read_b128 v[220:223], v163 offset:56320
	global_load_lds_dwordx4 v[152:153], off
	s_add_i32 m0, s22, 0x2000
	s_add_u32 s60, s60, 0x80080
	v_lshl_add_u64 v[152:153], v[230:231], 0, s[30:31]
	s_addc_u32 s61, s61, 0
	s_add_i32 s22, s64, s6
	global_load_lds_dwordx4 v[152:153], off
	s_waitcnt vmcnt(4)
	s_waitcnt lgkmcnt(0)
	s_barrier
	s_setprio 1
	s_waitcnt lgkmcnt(0)
	v_mfma_f32_16x16x32_bf16 v[62:65], v[144:147], v[188:191], v[62:65]
	v_mfma_f32_16x16x32_bf16 v[58:61], v[164:167], v[188:191], v[58:61]
	v_mfma_f32_16x16x32_bf16 v[46:49], v[144:147], v[200:203], v[46:49]
	v_mfma_f32_16x16x32_bf16 v[42:45], v[164:167], v[200:203], v[42:45]
	v_mfma_f32_16x16x32_bf16 v[30:33], v[144:147], v[208:211], v[30:33]
	v_mfma_f32_16x16x32_bf16 v[26:29], v[164:167], v[208:211], v[26:29]
	v_lshl_add_u64 v[152:153], s[60:61], 0, v[66:67]
	s_mov_b32 m0, s22
	s_nop 0
	global_load_lds_dwordx4 v[152:153], off
	v_mfma_f32_16x16x32_bf16 v[14:17], v[144:147], v[216:219], v[14:17]
	v_mfma_f32_16x16x32_bf16 v[10:13], v[164:167], v[216:219], v[10:13]
	v_mfma_f32_16x16x32_bf16 v[62:65], v[148:151], v[192:195], v[62:65]
	v_mfma_f32_16x16x32_bf16 v[58:61], v[168:171], v[192:195], v[58:61]
	v_mfma_f32_16x16x32_bf16 v[46:49], v[148:151], v[204:207], v[46:49]
	v_mfma_f32_16x16x32_bf16 v[42:45], v[168:171], v[204:207], v[42:45]
	v_lshl_add_u64 v[152:153], s[60:61], 0, v[136:137]
	s_add_i32 m0, s22, 0x2000
	s_nop 0
	global_load_lds_dwordx4 v[152:153], off
	v_mfma_f32_16x16x32_bf16 v[30:33], v[148:151], v[212:215], v[30:33]
	v_mfma_f32_16x16x32_bf16 v[26:29], v[168:171], v[212:215], v[26:29]
	v_mfma_f32_16x16x32_bf16 v[14:17], v[148:151], v[220:223], v[14:17]
	v_mfma_f32_16x16x32_bf16 v[10:13], v[168:171], v[220:223], v[10:13]
	s_setprio 0
	s_setprio 1
	v_mfma_f32_16x16x32_bf16 v[54:57], v[172:175], v[188:191], v[54:57]
	v_mfma_f32_16x16x32_bf16 v[50:53], v[180:183], v[188:191], v[50:53]
	v_lshl_add_u64 v[152:153], v[232:233], 0, s[30:31]
	s_mov_b32 m0, s16
	s_nop 0
	global_load_lds_dwordx4 v[152:153], off
	v_mfma_f32_16x16x32_bf16 v[38:41], v[172:175], v[200:203], v[38:41]
	v_mfma_f32_16x16x32_bf16 v[34:37], v[180:183], v[200:203], v[34:37]
	v_mfma_f32_16x16x32_bf16 v[22:25], v[172:175], v[208:211], v[22:25]
	v_mfma_f32_16x16x32_bf16 v[18:21], v[180:183], v[208:211], v[18:21]
	v_mfma_f32_16x16x32_bf16 v[6:9], v[172:175], v[216:219], v[6:9]
	v_mfma_f32_16x16x32_bf16 v[2:5], v[180:183], v[216:219], v[2:5]
	v_lshl_add_u64 v[152:153], v[234:235], 0, s[30:31]
	s_mov_b32 m0, s17
	s_nop 0
	global_load_lds_dwordx4 v[152:153], off
	v_mfma_f32_16x16x32_bf16 v[54:57], v[176:179], v[192:195], v[54:57]
	v_mfma_f32_16x16x32_bf16 v[50:53], v[184:187], v[192:195], v[50:53]
	v_mfma_f32_16x16x32_bf16 v[38:41], v[176:179], v[204:207], v[38:41]
	v_mfma_f32_16x16x32_bf16 v[34:37], v[184:187], v[204:207], v[34:37]
	v_mfma_f32_16x16x32_bf16 v[22:25], v[176:179], v[212:215], v[22:25]
	v_mfma_f32_16x16x32_bf16 v[18:21], v[184:187], v[212:215], v[18:21]
	v_mfma_f32_16x16x32_bf16 v[6:9], v[176:179], v[220:223], v[6:9]
	v_mfma_f32_16x16x32_bf16 v[2:5], v[184:187], v[220:223], v[2:5]
	s_setprio 0
	s_barrier
	s_add_u32 s58, s58, 0x100
	s_addc_u32 s59, s59, 0
	s_add_u32 s73, s73, 0x100
	s_addc_u32 s74, s74, 0
	s_cmp_ge_i32 s23, s20
	s_mov_b32 s22, s23
	s_cbranch_scc0 .LBB0_235
	s_and_b64 vcc, exec, s[40:41]
	s_cbranch_vccz .LBB0_238
	s_barrier

.LBB0_961:
	s_mov_b32 s14, s13
	s_add_i32 s13, s14, 1
	s_cmp_le_i32 s14, s12
	s_cbranch_scc1 .Latt_ctl_orig
	s_cmp_eq_u32 s14, s78
	s_cbranch_scc1 .Latt_ctl_orig
	s_branch .Latt_fast
.Latt_ctl_orig:
	s_cmp_ge_i32 s13, s77
	s_cbranch_scc1 .LBB0_963

.LBB0_963:
	s_cmp_lt_i32 s14, s12
	s_cbranch_scc1 .LBB0_981
	s_branch .Latt_gen_tile
.Latt_fast:
	s_and_b32 s15, s9, 0x4000
	s_max_i32 s20, s73, 0
	v_or_b32_e32 v246, s15, v220
	v_xor_b32_e32 v250, 0x80, v246
	v_xor_b32_e32 v247, 32, v246
	v_xor_b32_e32 v248, 64, v246
	s_sub_i32 s38, s73, 64
	s_max_i32 s74, s38, 0
	s_lshl_b64 s[16:17], s[74:75], 12
	s_add_i32 s38, s9, 0x4000
	s_and_b32 s38, s38, 0x4000
	s_add_i32 s39, s38, s10
	s_add_i32 s40, s39, 0x400
	s_add_i32 s41, s38, s11
	s_add_i32 s42, s41, 0x400
	s_mov_b64 s[44:45], 0x10000
	s_mov_b32 s43, m0
	s_cmp_le_i32 s12, 1
	s_cbranch_scc1 .Latt_fast_b
	s_cmp_eq_u32 s101, 0
	s_cbranch_scc1 .Latt_a_cold
	v_xor_b32_e32 v249, 0x60, v246
	v_xor_b32_e32 v251, 0xa0, v246
	v_xor_b32_e32 v252, 0xc0, v246
	v_xor_b32_e32 v253, 0xe0, v246
	v_add_u32_e32 v228, s15, v222
	s_mov_b32 s101, 0
	v_mfma_f32_32x32x16_bf16 v[116:131], v[180:183], v[238:241], v[116:131]
	v_lshl_add_u64 v[132:133], v[172:173], 0, s[16:17]
	s_mov_b32 m0, s39
	s_nop 0
	global_load_lds_dwordx4 v[132:133], off
	v_add_u32_e32 v148, s20, v216
	v_sub_u32_e32 v148, v148, v166
	v_mfma_f32_32x32x16_bf16 v[116:131], v[184:187], v[242:245], v[116:131]
	ds_read_b128 v[180:183], v250
	ds_read_b128 v[184:187], v219 offset:4096
	v_cvt_f32_i32_e32 v148, v148
	v_fma_f32 v148, v164, v148, -v221
	v_mfma_f32_32x32x16_bf16 v[84:99], v[188:191], v[238:241], v[84:99]
	v_lshl_add_u64 v[132:133], v[132:133], 0, v[66:67]
	s_mov_b32 m0, s40
	s_nop 0
	global_load_lds_dwordx4 v[132:133], off
	v_add_f32_e32 v149, v164, v148
	v_add_f32_e32 v150, v176, v148
	v_add_f32_e32 v151, v177, v149
	v_mfma_f32_32x32x16_bf16 v[84:99], v[192:195], v[242:245], v[84:99]
	ds_read_b128 v[188:191], v246
	ds_read_b128 v[192:195], v219
	v_add_f32_e32 v152, v174, v148
	v_add_f32_e32 v153, v175, v149
	v_add_f32_e32 v154, v174, v150
	v_add_f32_e32 v155, v175, v151
	v_mfma_f32_32x32x16_bf16 v[50:65], v[200:203], v[238:241], v[50:65]
	v_lshl_add_u64 v[134:135], v[168:169], 0, s[16:17]
	s_mov_b32 m0, s41
	s_nop 0
	global_load_lds_dwordx4 v[134:135], off
	v_add_f32_e32 v156, v174, v152
	v_add_f32_e32 v157, v175, v153
	v_add_f32_e32 v158, v174, v154
	v_add_f32_e32 v159, v175, v155
	v_mfma_f32_32x32x16_bf16 v[50:65], v[204:207], v[242:245], v[50:65]
	ds_read_b128 v[200:203], v247
	ds_read_b128 v[204:207], v219 offset:1024
	v_add_f32_e32 v160, v174, v156
	v_add_f32_e32 v161, v175, v157
	v_add_f32_e32 v162, v174, v158
	v_add_f32_e32 v163, v175, v159
	v_mfma_f32_32x32x16_bf16 v[2:17], v[208:211], v[238:241], v[2:17]
	v_lshl_add_u64 v[134:135], v[134:135], 0, s[44:45]
	s_mov_b32 m0, s42
	s_nop 0
	global_load_lds_dwordx4 v[134:135], off
	s_mov_b32 m0, s43
	v_mfma_f32_32x32x16_bf16 v[2:17], v[212:215], v[242:245], v[2:17]
	ds_read_b128 v[208:211], v248
	ds_read_b128 v[212:215], v219 offset:2048
	s_setprio 0
	s_branch .Latt_a_main
.Latt_a_cold:
	ds_read_b128 v[180:183], v250
	ds_read_b128 v[184:187], v219 offset:4096
	ds_read_b128 v[188:191], v246
	ds_read_b128 v[192:195], v219
	ds_read_b128 v[200:203], v247
	ds_read_b128 v[204:207], v219 offset:1024
	ds_read_b128 v[208:211], v248
	ds_read_b128 v[212:215], v219 offset:2048
	v_lshl_add_u64 v[132:133], v[172:173], 0, s[16:17]
	s_mov_b32 m0, s39
	s_nop 0
	global_load_lds_dwordx4 v[132:133], off
	v_lshl_add_u64 v[132:133], v[132:133], 0, v[66:67]
	s_mov_b32 m0, s40
	s_nop 0
	global_load_lds_dwordx4 v[132:133], off
	v_lshl_add_u64 v[134:135], v[168:169], 0, s[16:17]
	s_mov_b32 m0, s41
	s_nop 0
	global_load_lds_dwordx4 v[134:135], off
	v_lshl_add_u64 v[134:135], v[134:135], 0, s[44:45]
	s_mov_b32 m0, s42
	s_nop 0
	global_load_lds_dwordx4 v[134:135], off
	s_mov_b32 m0, s43
	v_add_u32_e32 v148, s20, v216
	v_sub_u32_e32 v148, v148, v166
	v_cvt_f32_i32_e32 v148, v148
	v_fma_f32 v148, v164, v148, -v221
	v_add_f32_e32 v149, v164, v148
	v_add_f32_e32 v150, v176, v148
	v_add_f32_e32 v151, v177, v149
	v_add_f32_e32 v152, v174, v148
	v_add_f32_e32 v153, v175, v149
	v_add_f32_e32 v154, v174, v150
	v_add_f32_e32 v155, v175, v151
	v_add_f32_e32 v156, v174, v152
	v_add_f32_e32 v157, v175, v153
	v_add_f32_e32 v158, v174, v154
	v_add_f32_e32 v159, v175, v155
	v_add_f32_e32 v160, v174, v156
	v_add_f32_e32 v161, v175, v157
	v_add_f32_e32 v162, v174, v158
	v_add_f32_e32 v163, v175, v159
	v_xor_b32_e32 v249, 0x60, v246
	v_xor_b32_e32 v251, 0xa0, v246
	v_xor_b32_e32 v252, 0xc0, v246
	v_xor_b32_e32 v253, 0xe0, v246
	v_add_u32_e32 v228, s15, v222
.Latt_a_main:
	s_waitcnt lgkmcnt(6)
	v_mfma_f32_32x32x16_bf16 v[132:147], v[180:183], v[184:187], v[148:163]
	ds_read_b128 v[180:183], v249
	ds_read_b128 v[184:187], v219 offset:3072
	s_waitcnt lgkmcnt(6)
	v_mfma_f32_32x32x16_bf16 v[148:163], v[188:191], v[192:195], v[148:163]
	ds_read_b128 v[188:191], v251
	ds_read_b128 v[192:195], v219 offset:5120
	s_waitcnt lgkmcnt(6)
	v_mfma_f32_32x32x16_bf16 v[148:163], v[200:203], v[204:207], v[148:163]
	ds_read_b128 v[200:203], v252
	ds_read_b128 v[204:207], v219 offset:6144
	s_waitcnt lgkmcnt(6)
	v_mfma_f32_32x32x16_bf16 v[148:163], v[208:211], v[212:215], v[148:163]
	ds_read_b128 v[208:211], v253
	ds_read_b128 v[212:215], v219 offset:7168
	s_waitcnt lgkmcnt(6)
	v_mfma_f32_32x32x16_bf16 v[148:163], v[180:183], v[184:187], v[148:163]
	ds_read_b64_tr_b16 v[180:181], v228 offset:32768
	ds_read_b64_tr_b16 v[182:183], v228 offset:33280
	ds_read_b64_tr_b16 v[184:185], v228 offset:33792
	ds_read_b64_tr_b16 v[186:187], v228 offset:34304
	s_waitcnt lgkmcnt(8)
	v_mfma_f32_32x32x16_bf16 v[132:147], v[188:191], v[192:195], v[132:147]
	ds_read_b64_tr_b16 v[188:189], v228 offset:36864
	ds_read_b64_tr_b16 v[190:191], v228 offset:37376
	ds_read_b64_tr_b16 v[192:193], v228 offset:37888
	ds_read_b64_tr_b16 v[194:195], v228 offset:38400
	s_waitcnt lgkmcnt(10)
	v_mfma_f32_32x32x16_bf16 v[132:147], v[200:203], v[204:207], v[132:147]
	ds_read_b64_tr_b16 v[200:201], v228 offset:40960
	ds_read_b64_tr_b16 v[202:203], v228 offset:41472
	ds_read_b64_tr_b16 v[204:205], v228 offset:41984
	ds_read_b64_tr_b16 v[206:207], v228 offset:42496
	s_waitcnt lgkmcnt(12)
	v_mfma_f32_32x32x16_bf16 v[132:147], v[208:211], v[212:215], v[132:147]
	ds_read_b64_tr_b16 v[208:209], v228 offset:45056
	ds_read_b64_tr_b16 v[210:211], v228 offset:45568
	v_exp_f32_e32 v148, v148
	v_exp_f32_e32 v149, v149
	v_exp_f32_e32 v150, v150
	v_exp_f32_e32 v151, v151
	v_exp_f32_e32 v152, v152
	v_exp_f32_e32 v153, v153
	v_exp_f32_e32 v154, v154
	v_exp_f32_e32 v155, v155
	v_exp_f32_e32 v156, v156
	v_exp_f32_e32 v157, v157
	v_exp_f32_e32 v158, v158
	v_exp_f32_e32 v159, v159
	v_exp_f32_e32 v160, v160
	v_exp_f32_e32 v161, v161
	v_exp_f32_e32 v162, v162
	v_exp_f32_e32 v163, v163
	v_add_f32_e32 v170, v170, v148
	v_add_f32_e32 v171, v171, v149
	v_cvt_pk_bf16_f32 v230, v148, v149
	v_add_f32_e32 v170, v170, v150
	v_add_f32_e32 v171, v171, v151
	v_cvt_pk_bf16_f32 v231, v150, v151
	v_add_f32_e32 v170, v170, v152
	v_add_f32_e32 v171, v171, v153
	v_cvt_pk_bf16_f32 v232, v152, v153
	v_add_f32_e32 v170, v170, v154
	v_add_f32_e32 v171, v171, v155
	v_cvt_pk_bf16_f32 v233, v154, v155
	v_add_f32_e32 v170, v170, v156
	v_add_f32_e32 v171, v171, v157
	v_cvt_pk_bf16_f32 v234, v156, v157
	v_add_f32_e32 v170, v170, v158
	v_add_f32_e32 v171, v171, v159
	v_cvt_pk_bf16_f32 v235, v158, v159
	v_add_f32_e32 v170, v170, v160
	v_add_f32_e32 v171, v171, v161
	v_cvt_pk_bf16_f32 v236, v160, v161
	v_add_f32_e32 v170, v170, v162
	v_add_f32_e32 v171, v171, v163
	v_cvt_pk_bf16_f32 v237, v162, v163
	s_waitcnt lgkmcnt(12)
	ds_read_b64_tr_b16 v[212:213], v228 offset:46080
	ds_read_b64_tr_b16 v[214:215], v228 offset:46592
	s_setprio 2
	v_mfma_f32_32x32x16_bf16 v[100:115], v[180:183], v[230:233], v[100:115]
	v_exp_f32_e32 v132, v132
	v_exp_f32_e32 v133, v133
	s_waitcnt lgkmcnt(12)
	v_mfma_f32_32x32x16_bf16 v[100:115], v[184:187], v[234:237], v[100:115]
	v_exp_f32_e32 v134, v134
	v_exp_f32_e32 v135, v135
	v_add_f32_e32 v178, v178, v132
	v_add_f32_e32 v179, v179, v133
	v_cvt_pk_bf16_f32 v238, v132, v133
	s_waitcnt lgkmcnt(10)
	v_mfma_f32_32x32x16_bf16 v[68:83], v[188:191], v[230:233], v[68:83]
	v_exp_f32_e32 v136, v136
	v_exp_f32_e32 v137, v137
	v_add_f32_e32 v178, v178, v134
	v_add_f32_e32 v179, v179, v135
	v_cvt_pk_bf16_f32 v239, v134, v135
	s_waitcnt lgkmcnt(8)
	v_mfma_f32_32x32x16_bf16 v[68:83], v[192:195], v[234:237], v[68:83]
	v_exp_f32_e32 v138, v138
	v_exp_f32_e32 v139, v139
	v_add_f32_e32 v178, v178, v136
	v_add_f32_e32 v179, v179, v137
	v_cvt_pk_bf16_f32 v240, v136, v137
	s_waitcnt lgkmcnt(6)
	v_mfma_f32_32x32x16_bf16 v[34:49], v[200:203], v[230:233], v[34:49]
	v_exp_f32_e32 v140, v140
	v_exp_f32_e32 v141, v141
	v_add_f32_e32 v178, v178, v138
	v_add_f32_e32 v179, v179, v139
	v_cvt_pk_bf16_f32 v241, v138, v139
	s_waitcnt lgkmcnt(4)
	v_mfma_f32_32x32x16_bf16 v[34:49], v[204:207], v[234:237], v[34:49]
	v_exp_f32_e32 v142, v142
	v_exp_f32_e32 v143, v143
	v_add_f32_e32 v178, v178, v140
	v_add_f32_e32 v179, v179, v141
	v_cvt_pk_bf16_f32 v242, v140, v141
	s_waitcnt lgkmcnt(2)
	v_mfma_f32_32x32x16_bf16 v[18:33], v[208:211], v[230:233], v[18:33]
	v_exp_f32_e32 v144, v144
	v_exp_f32_e32 v145, v145
	v_add_f32_e32 v178, v178, v142
	v_add_f32_e32 v179, v179, v143
	v_cvt_pk_bf16_f32 v243, v142, v143
	s_waitcnt lgkmcnt(0)
	v_mfma_f32_32x32x16_bf16 v[18:33], v[212:215], v[234:237], v[18:33]
	v_exp_f32_e32 v146, v146
	v_exp_f32_e32 v147, v147
	v_add_f32_e32 v178, v178, v144
	v_add_f32_e32 v179, v179, v145
	v_cvt_pk_bf16_f32 v244, v144, v145
	s_nop 0
	v_add_f32_e32 v178, v178, v146
	v_add_f32_e32 v179, v179, v147
	v_cvt_pk_bf16_f32 v245, v146, v147
	v_mfma_f32_32x32x16_bf16 v[116:131], v[180:183], v[238:241], v[116:131]
	v_add3_u32 v148, s20, v216, 32
	v_sub_u32_e32 v148, v148, v166
	v_mfma_f32_32x32x16_bf16 v[116:131], v[184:187], v[242:245], v[116:131]
	ds_read_b128 v[180:183], v250 offset:8192
	ds_read_b128 v[184:187], v219 offset:4096
	v_cvt_f32_i32_e32 v148, v148
	v_fma_f32 v148, v164, v148, -v221
	v_mfma_f32_32x32x16_bf16 v[84:99], v[188:191], v[238:241], v[84:99]
	v_add_f32_e32 v149, v164, v148
	v_add_f32_e32 v150, v176, v148
	v_add_f32_e32 v151, v177, v149
	v_mfma_f32_32x32x16_bf16 v[84:99], v[192:195], v[242:245], v[84:99]
	ds_read_b128 v[188:191], v246 offset:8192
	ds_read_b128 v[192:195], v219
	v_add_f32_e32 v152, v174, v148
	v_add_f32_e32 v153, v175, v149
	v_add_f32_e32 v154, v174, v150
	v_add_f32_e32 v155, v175, v151
	v_mfma_f32_32x32x16_bf16 v[50:65], v[200:203], v[238:241], v[50:65]
	v_add_f32_e32 v156, v174, v152
	v_add_f32_e32 v157, v175, v153
	v_add_f32_e32 v158, v174, v154
	v_add_f32_e32 v159, v175, v155
	v_mfma_f32_32x32x16_bf16 v[50:65], v[204:207], v[242:245], v[50:65]
	ds_read_b128 v[200:203], v247 offset:8192
	ds_read_b128 v[204:207], v219 offset:1024
	v_add_f32_e32 v160, v174, v156
	v_add_f32_e32 v161, v175, v157
	v_add_f32_e32 v162, v174, v158
	v_add_f32_e32 v163, v175, v159
	v_mfma_f32_32x32x16_bf16 v[2:17], v[208:211], v[238:241], v[2:17]
	v_mfma_f32_32x32x16_bf16 v[2:17], v[212:215], v[242:245], v[2:17]
	ds_read_b128 v[208:211], v248 offset:8192
	ds_read_b128 v[212:215], v219 offset:2048
	s_setprio 0
	s_waitcnt lgkmcnt(6)
	v_mfma_f32_32x32x16_bf16 v[132:147], v[180:183], v[184:187], v[148:163]
	ds_read_b128 v[180:183], v249 offset:8192
	ds_read_b128 v[184:187], v219 offset:3072
	s_waitcnt lgkmcnt(6)
	v_mfma_f32_32x32x16_bf16 v[148:163], v[188:191], v[192:195], v[148:163]
	ds_read_b128 v[188:191], v251 offset:8192
	ds_read_b128 v[192:195], v219 offset:5120
	s_waitcnt lgkmcnt(6)
	v_mfma_f32_32x32x16_bf16 v[148:163], v[200:203], v[204:207], v[148:163]
	ds_read_b128 v[200:203], v252 offset:8192
	ds_read_b128 v[204:207], v219 offset:6144
	s_waitcnt lgkmcnt(6)
	v_mfma_f32_32x32x16_bf16 v[148:163], v[208:211], v[212:215], v[148:163]
	ds_read_b128 v[208:211], v253 offset:8192
	ds_read_b128 v[212:215], v219 offset:7168
	s_waitcnt lgkmcnt(6)
	v_mfma_f32_32x32x16_bf16 v[148:163], v[180:183], v[184:187], v[148:163]
	ds_read_b64_tr_b16 v[180:181], v228 offset:34816
	ds_read_b64_tr_b16 v[182:183], v228 offset:35328
	ds_read_b64_tr_b16 v[184:185], v228 offset:35840
	ds_read_b64_tr_b16 v[186:187], v228 offset:36352
	s_waitcnt lgkmcnt(8)
	v_mfma_f32_32x32x16_bf16 v[132:147], v[188:191], v[192:195], v[132:147]
	ds_read_b64_tr_b16 v[188:189], v228 offset:38912
	ds_read_b64_tr_b16 v[190:191], v228 offset:39424
	ds_read_b64_tr_b16 v[192:193], v228 offset:39936
	ds_read_b64_tr_b16 v[194:195], v228 offset:40448
	s_waitcnt lgkmcnt(10)
	v_mfma_f32_32x32x16_bf16 v[132:147], v[200:203], v[204:207], v[132:147]
	ds_read_b64_tr_b16 v[200:201], v228 offset:43008
	ds_read_b64_tr_b16 v[202:203], v228 offset:43520
	ds_read_b64_tr_b16 v[204:205], v228 offset:44032
	ds_read_b64_tr_b16 v[206:207], v228 offset:44544
	s_waitcnt lgkmcnt(12)
	v_mfma_f32_32x32x16_bf16 v[132:147], v[208:211], v[212:215], v[132:147]
	ds_read_b64_tr_b16 v[208:209], v228 offset:47104
	ds_read_b64_tr_b16 v[210:211], v228 offset:47616
	v_exp_f32_e32 v148, v148
	v_exp_f32_e32 v149, v149
	v_exp_f32_e32 v150, v150
	v_exp_f32_e32 v151, v151
	v_exp_f32_e32 v152, v152
	v_exp_f32_e32 v153, v153
	v_exp_f32_e32 v154, v154
	v_exp_f32_e32 v155, v155
	v_exp_f32_e32 v156, v156
	v_exp_f32_e32 v157, v157
	v_exp_f32_e32 v158, v158
	v_exp_f32_e32 v159, v159
	v_exp_f32_e32 v160, v160
	v_exp_f32_e32 v161, v161
	v_exp_f32_e32 v162, v162
	v_exp_f32_e32 v163, v163
	v_add_f32_e32 v170, v170, v148
	v_add_f32_e32 v171, v171, v149
	v_cvt_pk_bf16_f32 v230, v148, v149
	v_add_f32_e32 v170, v170, v150
	v_add_f32_e32 v171, v171, v151
	v_cvt_pk_bf16_f32 v231, v150, v151
	v_add_f32_e32 v170, v170, v152
	v_add_f32_e32 v171, v171, v153
	v_cvt_pk_bf16_f32 v232, v152, v153
	v_add_f32_e32 v170, v170, v154
	v_add_f32_e32 v171, v171, v155
	v_cvt_pk_bf16_f32 v233, v154, v155
	v_add_f32_e32 v170, v170, v156
	v_add_f32_e32 v171, v171, v157
	v_cvt_pk_bf16_f32 v234, v156, v157
	v_add_f32_e32 v170, v170, v158
	v_add_f32_e32 v171, v171, v159
	v_cvt_pk_bf16_f32 v235, v158, v159
	v_add_f32_e32 v170, v170, v160
	v_add_f32_e32 v171, v171, v161
	v_cvt_pk_bf16_f32 v236, v160, v161
	v_add_f32_e32 v170, v170, v162
	v_add_f32_e32 v171, v171, v163
	v_cvt_pk_bf16_f32 v237, v162, v163
	s_waitcnt lgkmcnt(12)
	ds_read_b64_tr_b16 v[212:213], v228 offset:48128
	ds_read_b64_tr_b16 v[214:215], v228 offset:48640
	s_setprio 2
	v_mfma_f32_32x32x16_bf16 v[100:115], v[180:183], v[230:233], v[100:115]
	v_exp_f32_e32 v132, v132
	v_exp_f32_e32 v133, v133
	s_waitcnt lgkmcnt(12)
	v_mfma_f32_32x32x16_bf16 v[100:115], v[184:187], v[234:237], v[100:115]
	v_exp_f32_e32 v134, v134
	v_exp_f32_e32 v135, v135
	v_add_f32_e32 v178, v178, v132
	v_add_f32_e32 v179, v179, v133
	v_cvt_pk_bf16_f32 v238, v132, v133
	s_waitcnt lgkmcnt(10)
	v_mfma_f32_32x32x16_bf16 v[68:83], v[188:191], v[230:233], v[68:83]
	v_exp_f32_e32 v136, v136
	v_exp_f32_e32 v137, v137
	v_add_f32_e32 v178, v178, v134
	v_add_f32_e32 v179, v179, v135
	v_cvt_pk_bf16_f32 v239, v134, v135
	s_waitcnt lgkmcnt(8)
	v_mfma_f32_32x32x16_bf16 v[68:83], v[192:195], v[234:237], v[68:83]
	v_exp_f32_e32 v138, v138
	v_exp_f32_e32 v139, v139
	v_add_f32_e32 v178, v178, v136
	v_add_f32_e32 v179, v179, v137
	v_cvt_pk_bf16_f32 v240, v136, v137
	s_waitcnt lgkmcnt(6)
	v_mfma_f32_32x32x16_bf16 v[34:49], v[200:203], v[230:233], v[34:49]
	v_exp_f32_e32 v140, v140
	v_exp_f32_e32 v141, v141
	v_add_f32_e32 v178, v178, v138
	v_add_f32_e32 v179, v179, v139
	v_cvt_pk_bf16_f32 v241, v138, v139
	s_waitcnt lgkmcnt(4)
	v_mfma_f32_32x32x16_bf16 v[34:49], v[204:207], v[234:237], v[34:49]
	v_exp_f32_e32 v142, v142
	v_exp_f32_e32 v143, v143
	v_add_f32_e32 v178, v178, v140
	v_add_f32_e32 v179, v179, v141
	v_cvt_pk_bf16_f32 v242, v140, v141
	s_waitcnt lgkmcnt(2)
	v_mfma_f32_32x32x16_bf16 v[18:33], v[208:211], v[230:233], v[18:33]
	v_exp_f32_e32 v144, v144
	v_exp_f32_e32 v145, v145
	v_add_f32_e32 v178, v178, v142
	v_add_f32_e32 v179, v179, v143
	v_cvt_pk_bf16_f32 v243, v142, v143
	s_waitcnt lgkmcnt(0)
	v_mfma_f32_32x32x16_bf16 v[18:33], v[212:215], v[234:237], v[18:33]
	v_exp_f32_e32 v146, v146
	v_exp_f32_e32 v147, v147
	v_add_f32_e32 v178, v178, v144
	v_add_f32_e32 v179, v179, v145
	v_cvt_pk_bf16_f32 v244, v144, v145
	s_nop 0
	v_add_f32_e32 v178, v178, v146
	v_add_f32_e32 v179, v179, v147
	v_cvt_pk_bf16_f32 v245, v146, v147
	s_cmp_ge_i32 s13, s77
	s_cbranch_scc1 .Latt_a_flush
	s_cmp_eq_u32 s13, s78
	s_cbranch_scc1 .Latt_a_flush
	s_mov_b32 s101, 1
	s_branch .LBB0_981
.Latt_a_flush:
	v_mfma_f32_32x32x16_bf16 v[116:131], v[180:183], v[238:241], v[116:131]
	v_mfma_f32_32x32x16_bf16 v[116:131], v[184:187], v[242:245], v[116:131]
	v_mfma_f32_32x32x16_bf16 v[84:99], v[188:191], v[238:241], v[84:99]
	v_mfma_f32_32x32x16_bf16 v[84:99], v[192:195], v[242:245], v[84:99]
	v_mfma_f32_32x32x16_bf16 v[50:65], v[200:203], v[238:241], v[50:65]
	v_mfma_f32_32x32x16_bf16 v[50:65], v[204:207], v[242:245], v[50:65]
	v_mfma_f32_32x32x16_bf16 v[2:17], v[208:211], v[238:241], v[2:17]
	v_mfma_f32_32x32x16_bf16 v[2:17], v[212:215], v[242:245], v[2:17]
	s_setprio 0
	s_branch .LBB0_981
.Latt_fast_b:
	s_cmp_eq_u32 s101, 0
	s_cbranch_scc1 .Latt_b_cold
	v_xor_b32_e32 v249, 0x60, v246
	v_xor_b32_e32 v251, 0xa0, v246
	v_xor_b32_e32 v252, 0xc0, v246
	v_xor_b32_e32 v253, 0xe0, v246
	v_add_u32_e32 v228, s15, v222
	s_mov_b32 s101, 0
	s_setprio 2
	v_mfma_f32_32x32x16_bf16 v[100:115], v[180:183], v[230:233], v[100:115]
	v_exp_f32_e32 v132, v132
	v_exp_f32_e32 v133, v133
	s_waitcnt lgkmcnt(12)
	v_mfma_f32_32x32x16_bf16 v[100:115], v[184:187], v[234:237], v[100:115]
	v_exp_f32_e32 v134, v134
	v_exp_f32_e32 v135, v135
	v_add_f32_e32 v178, v178, v132
	v_add_f32_e32 v179, v179, v133
	v_cvt_pk_bf16_f32 v238, v132, v133
	s_waitcnt lgkmcnt(10)
	v_mfma_f32_32x32x16_bf16 v[68:83], v[188:191], v[230:233], v[68:83]
	v_exp_f32_e32 v136, v136
	v_exp_f32_e32 v137, v137
	v_add_f32_e32 v178, v178, v134
	v_add_f32_e32 v179, v179, v135
	v_cvt_pk_bf16_f32 v239, v134, v135
	s_waitcnt lgkmcnt(8)
	v_mfma_f32_32x32x16_bf16 v[68:83], v[192:195], v[234:237], v[68:83]
	v_exp_f32_e32 v138, v138
	v_exp_f32_e32 v139, v139
	v_add_f32_e32 v178, v178, v136
	v_add_f32_e32 v179, v179, v137
	v_cvt_pk_bf16_f32 v240, v136, v137
	s_waitcnt lgkmcnt(6)
	v_mfma_f32_32x32x16_bf16 v[34:49], v[200:203], v[230:233], v[34:49]
	v_exp_f32_e32 v140, v140
	v_exp_f32_e32 v141, v141
	v_add_f32_e32 v178, v178, v138
	v_add_f32_e32 v179, v179, v139
	v_cvt_pk_bf16_f32 v241, v138, v139
	s_waitcnt lgkmcnt(4)
	v_mfma_f32_32x32x16_bf16 v[34:49], v[204:207], v[234:237], v[34:49]
	v_exp_f32_e32 v142, v142
	v_exp_f32_e32 v143, v143
	v_add_f32_e32 v178, v178, v140
	v_add_f32_e32 v179, v179, v141
	v_cvt_pk_bf16_f32 v242, v140, v141
	s_waitcnt lgkmcnt(2)
	v_mfma_f32_32x32x16_bf16 v[18:33], v[208:211], v[230:233], v[18:33]
	v_exp_f32_e32 v144, v144
	v_exp_f32_e32 v145, v145
	v_add_f32_e32 v178, v178, v142
	v_add_f32_e32 v179, v179, v143
	v_cvt_pk_bf16_f32 v243, v142, v143
	s_waitcnt lgkmcnt(0)
	v_mfma_f32_32x32x16_bf16 v[18:33], v[212:215], v[234:237], v[18:33]
	v_exp_f32_e32 v146, v146
	v_exp_f32_e32 v147, v147
	v_add_f32_e32 v178, v178, v144
	v_add_f32_e32 v179, v179, v145
	v_cvt_pk_bf16_f32 v244, v144, v145
	s_nop 0
	v_add_f32_e32 v178, v178, v146
	v_add_f32_e32 v179, v179, v147
	v_cvt_pk_bf16_f32 v245, v146, v147
	v_mfma_f32_32x32x16_bf16 v[116:131], v[180:183], v[238:241], v[116:131]
	v_lshl_add_u64 v[132:133], v[172:173], 0, s[16:17]
	s_mov_b32 m0, s39
	s_nop 0
	global_load_lds_dwordx4 v[132:133], off
	v_add_u32_e32 v148, s20, v216
	v_sub_u32_e32 v148, v148, v166
	v_mfma_f32_32x32x16_bf16 v[116:131], v[184:187], v[242:245], v[116:131]
	ds_read_b128 v[180:183], v250
	ds_read_b128 v[184:187], v219 offset:4096
	v_cvt_f32_i32_e32 v148, v148
	v_fma_f32 v148, v164, v148, -v221
	v_mfma_f32_32x32x16_bf16 v[84:99], v[188:191], v[238:241], v[84:99]
	v_lshl_add_u64 v[132:133], v[132:133], 0, v[66:67]
	s_mov_b32 m0, s40
	s_nop 0
	global_load_lds_dwordx4 v[132:133], off
	v_add_f32_e32 v149, v164, v148
	v_add_f32_e32 v150, v176, v148
	v_add_f32_e32 v151, v177, v149
	v_mfma_f32_32x32x16_bf16 v[84:99], v[192:195], v[242:245], v[84:99]
	ds_read_b128 v[188:191], v246
	ds_read_b128 v[192:195], v219
	v_add_f32_e32 v152, v174, v148
	v_add_f32_e32 v153, v175, v149
	v_add_f32_e32 v154, v174, v150
	v_add_f32_e32 v155, v175, v151
	v_mfma_f32_32x32x16_bf16 v[50:65], v[200:203], v[238:241], v[50:65]
	v_lshl_add_u64 v[134:135], v[168:169], 0, s[16:17]
	s_mov_b32 m0, s41
	s_nop 0
	global_load_lds_dwordx4 v[134:135], off
	v_add_f32_e32 v156, v174, v152
	v_add_f32_e32 v157, v175, v153
	v_add_f32_e32 v158, v174, v154
	v_add_f32_e32 v159, v175, v155
	v_mfma_f32_32x32x16_bf16 v[50:65], v[204:207], v[242:245], v[50:65]
	ds_read_b128 v[200:203], v247
	ds_read_b128 v[204:207], v219 offset:1024
	v_add_f32_e32 v160, v174, v156
	v_add_f32_e32 v161, v175, v157
	v_add_f32_e32 v162, v174, v158
	v_add_f32_e32 v163, v175, v159
	v_mfma_f32_32x32x16_bf16 v[2:17], v[208:211], v[238:241], v[2:17]
	v_lshl_add_u64 v[134:135], v[134:135], 0, s[44:45]
	s_mov_b32 m0, s42
	s_nop 0
	global_load_lds_dwordx4 v[134:135], off
	s_mov_b32 m0, s43
	v_mfma_f32_32x32x16_bf16 v[2:17], v[212:215], v[242:245], v[2:17]
	ds_read_b128 v[208:211], v248
	ds_read_b128 v[212:215], v219 offset:2048
	s_setprio 0
	s_branch .Latt_b_main

.Latt_b_main:
	s_waitcnt lgkmcnt(6)
	v_mfma_f32_32x32x16_bf16 v[132:147], v[180:183], v[184:187], v[148:163]
	ds_read_b128 v[180:183], v249
	ds_read_b128 v[184:187], v219 offset:3072
	s_waitcnt lgkmcnt(6)
	v_mfma_f32_32x32x16_bf16 v[148:163], v[188:191], v[192:195], v[148:163]
	ds_read_b128 v[188:191], v251
	ds_read_b128 v[192:195], v219 offset:5120
	s_waitcnt lgkmcnt(6)
	v_mfma_f32_32x32x16_bf16 v[148:163], v[200:203], v[204:207], v[148:163]
	ds_read_b128 v[200:203], v252
	ds_read_b128 v[204:207], v219 offset:6144
	s_waitcnt lgkmcnt(6)
	v_mfma_f32_32x32x16_bf16 v[148:163], v[208:211], v[212:215], v[148:163]
	ds_read_b128 v[208:211], v253
	ds_read_b128 v[212:215], v219 offset:7168
	s_waitcnt lgkmcnt(6)
	v_mfma_f32_32x32x16_bf16 v[148:163], v[180:183], v[184:187], v[148:163]
	ds_read_b64_tr_b16 v[180:181], v228 offset:32768
	ds_read_b64_tr_b16 v[182:183], v228 offset:33280
	ds_read_b64_tr_b16 v[184:185], v228 offset:33792
	ds_read_b64_tr_b16 v[186:187], v228 offset:34304
	s_waitcnt lgkmcnt(8)
	v_mfma_f32_32x32x16_bf16 v[132:147], v[188:191], v[192:195], v[132:147]
	ds_read_b64_tr_b16 v[188:189], v228 offset:36864
	ds_read_b64_tr_b16 v[190:191], v228 offset:37376
	ds_read_b64_tr_b16 v[192:193], v228 offset:37888
	ds_read_b64_tr_b16 v[194:195], v228 offset:38400
	s_waitcnt lgkmcnt(10)
	v_mfma_f32_32x32x16_bf16 v[132:147], v[200:203], v[204:207], v[132:147]
	ds_read_b64_tr_b16 v[200:201], v228 offset:40960
	ds_read_b64_tr_b16 v[202:203], v228 offset:41472
	ds_read_b64_tr_b16 v[204:205], v228 offset:41984
	ds_read_b64_tr_b16 v[206:207], v228 offset:42496
	s_waitcnt lgkmcnt(12)
	v_mfma_f32_32x32x16_bf16 v[132:147], v[208:211], v[212:215], v[132:147]
	ds_read_b64_tr_b16 v[208:209], v228 offset:45056
	ds_read_b64_tr_b16 v[210:211], v228 offset:45568
	v_exp_f32_e32 v148, v148
	v_exp_f32_e32 v149, v149
	v_exp_f32_e32 v150, v150
	v_exp_f32_e32 v151, v151
	v_exp_f32_e32 v152, v152
	v_exp_f32_e32 v153, v153
	v_exp_f32_e32 v154, v154
	v_exp_f32_e32 v155, v155
	v_exp_f32_e32 v156, v156
	v_exp_f32_e32 v157, v157
	v_exp_f32_e32 v158, v158
	v_exp_f32_e32 v159, v159
	v_exp_f32_e32 v160, v160
	v_exp_f32_e32 v161, v161
	v_exp_f32_e32 v162, v162
	v_exp_f32_e32 v163, v163
	v_add_f32_e32 v170, v170, v148
	v_add_f32_e32 v171, v171, v149
	v_cvt_pk_bf16_f32 v230, v148, v149
	v_add_f32_e32 v170, v170, v150
	v_add_f32_e32 v171, v171, v151
	v_cvt_pk_bf16_f32 v231, v150, v151
	v_add_f32_e32 v170, v170, v152
	v_add_f32_e32 v171, v171, v153
	v_cvt_pk_bf16_f32 v232, v152, v153
	v_add_f32_e32 v170, v170, v154
	v_add_f32_e32 v171, v171, v155
	v_cvt_pk_bf16_f32 v233, v154, v155
	v_add_f32_e32 v170, v170, v156
	v_add_f32_e32 v171, v171, v157
	v_cvt_pk_bf16_f32 v234, v156, v157
	v_add_f32_e32 v170, v170, v158
	v_add_f32_e32 v171, v171, v159
	v_cvt_pk_bf16_f32 v235, v158, v159
	v_add_f32_e32 v170, v170, v160
	v_add_f32_e32 v171, v171, v161
	v_cvt_pk_bf16_f32 v236, v160, v161
	v_add_f32_e32 v170, v170, v162
	v_add_f32_e32 v171, v171, v163
	v_cvt_pk_bf16_f32 v237, v162, v163
	s_waitcnt lgkmcnt(12)
	ds_read_b64_tr_b16 v[212:213], v228 offset:46080
	ds_read_b64_tr_b16 v[214:215], v228 offset:46592
	s_setprio 2
	v_mfma_f32_32x32x16_bf16 v[100:115], v[180:183], v[230:233], v[100:115]
	v_exp_f32_e32 v132, v132
	v_exp_f32_e32 v133, v133
	s_waitcnt lgkmcnt(12)
	v_mfma_f32_32x32x16_bf16 v[100:115], v[184:187], v[234:237], v[100:115]
	v_exp_f32_e32 v134, v134
	v_exp_f32_e32 v135, v135
	v_add_f32_e32 v178, v178, v132
	v_add_f32_e32 v179, v179, v133
	v_cvt_pk_bf16_f32 v238, v132, v133
	s_waitcnt lgkmcnt(10)
	v_mfma_f32_32x32x16_bf16 v[68:83], v[188:191], v[230:233], v[68:83]
	v_exp_f32_e32 v136, v136
	v_exp_f32_e32 v137, v137
	v_add_f32_e32 v178, v178, v134
	v_add_f32_e32 v179, v179, v135
	v_cvt_pk_bf16_f32 v239, v134, v135
	s_waitcnt lgkmcnt(8)
	v_mfma_f32_32x32x16_bf16 v[68:83], v[192:195], v[234:237], v[68:83]
	v_exp_f32_e32 v138, v138
	v_exp_f32_e32 v139, v139
	v_add_f32_e32 v178, v178, v136
	v_add_f32_e32 v179, v179, v137
	v_cvt_pk_bf16_f32 v240, v136, v137
	s_waitcnt lgkmcnt(6)
	v_mfma_f32_32x32x16_bf16 v[34:49], v[200:203], v[230:233], v[34:49]
	v_exp_f32_e32 v140, v140
	v_exp_f32_e32 v141, v141
	v_add_f32_e32 v178, v178, v138
	v_add_f32_e32 v179, v179, v139
	v_cvt_pk_bf16_f32 v241, v138, v139
	s_waitcnt lgkmcnt(4)
	v_mfma_f32_32x32x16_bf16 v[34:49], v[204:207], v[234:237], v[34:49]
	v_exp_f32_e32 v142, v142
	v_exp_f32_e32 v143, v143
	v_add_f32_e32 v178, v178, v140
	v_add_f32_e32 v179, v179, v141
	v_cvt_pk_bf16_f32 v242, v140, v141
	s_waitcnt lgkmcnt(2)
	v_mfma_f32_32x32x16_bf16 v[18:33], v[208:211], v[230:233], v[18:33]
	v_exp_f32_e32 v144, v144
	v_exp_f32_e32 v145, v145
	v_add_f32_e32 v178, v178, v142
	v_add_f32_e32 v179, v179, v143
	v_cvt_pk_bf16_f32 v243, v142, v143
	s_waitcnt lgkmcnt(0)
	v_mfma_f32_32x32x16_bf16 v[18:33], v[212:215], v[234:237], v[18:33]
	v_exp_f32_e32 v146, v146
	v_exp_f32_e32 v147, v147
	v_add_f32_e32 v178, v178, v144
	v_add_f32_e32 v179, v179, v145
	v_cvt_pk_bf16_f32 v244, v144, v145
	s_nop 0
	v_add_f32_e32 v178, v178, v146
	v_add_f32_e32 v179, v179, v147
	v_cvt_pk_bf16_f32 v245, v146, v147
	v_mfma_f32_32x32x16_bf16 v[116:131], v[180:183], v[238:241], v[116:131]
	v_add3_u32 v148, s20, v216, 32
	v_sub_u32_e32 v148, v148, v166
	v_mfma_f32_32x32x16_bf16 v[116:131], v[184:187], v[242:245], v[116:131]
	ds_read_b128 v[180:183], v250 offset:8192
	ds_read_b128 v[184:187], v219 offset:4096
	v_cvt_f32_i32_e32 v148, v148
	v_fma_f32 v148, v164, v148, -v221
	v_mfma_f32_32x32x16_bf16 v[84:99], v[188:191], v[238:241], v[84:99]
	v_add_f32_e32 v149, v164, v148
	v_add_f32_e32 v150, v176, v148
	v_add_f32_e32 v151, v177, v149
	v_mfma_f32_32x32x16_bf16 v[84:99], v[192:195], v[242:245], v[84:99]
	ds_read_b128 v[188:191], v246 offset:8192
	ds_read_b128 v[192:195], v219
	v_add_f32_e32 v152, v174, v148
	v_add_f32_e32 v153, v175, v149
	v_add_f32_e32 v154, v174, v150
	v_add_f32_e32 v155, v175, v151
	v_mfma_f32_32x32x16_bf16 v[50:65], v[200:203], v[238:241], v[50:65]
	v_add_f32_e32 v156, v174, v152
	v_add_f32_e32 v157, v175, v153
	v_add_f32_e32 v158, v174, v154
	v_add_f32_e32 v159, v175, v155
	v_mfma_f32_32x32x16_bf16 v[50:65], v[204:207], v[242:245], v[50:65]
	ds_read_b128 v[200:203], v247 offset:8192
	ds_read_b128 v[204:207], v219 offset:1024
	v_add_f32_e32 v160, v174, v156
	v_add_f32_e32 v161, v175, v157
	v_add_f32_e32 v162, v174, v158
	v_add_f32_e32 v163, v175, v159
	v_mfma_f32_32x32x16_bf16 v[2:17], v[208:211], v[238:241], v[2:17]
	v_mfma_f32_32x32x16_bf16 v[2:17], v[212:215], v[242:245], v[2:17]
	ds_read_b128 v[208:211], v248 offset:8192
	ds_read_b128 v[212:215], v219 offset:2048
	s_setprio 0
	s_waitcnt lgkmcnt(6)
	v_mfma_f32_32x32x16_bf16 v[132:147], v[180:183], v[184:187], v[148:163]
	ds_read_b128 v[180:183], v249 offset:8192
	ds_read_b128 v[184:187], v219 offset:3072
	s_waitcnt lgkmcnt(6)
	v_mfma_f32_32x32x16_bf16 v[148:163], v[188:191], v[192:195], v[148:163]
	ds_read_b128 v[188:191], v251 offset:8192
	ds_read_b128 v[192:195], v219 offset:5120
	s_waitcnt lgkmcnt(6)
	v_mfma_f32_32x32x16_bf16 v[148:163], v[200:203], v[204:207], v[148:163]
	ds_read_b128 v[200:203], v252 offset:8192
	ds_read_b128 v[204:207], v219 offset:6144
	s_waitcnt lgkmcnt(6)
	v_mfma_f32_32x32x16_bf16 v[148:163], v[208:211], v[212:215], v[148:163]
	ds_read_b128 v[208:211], v253 offset:8192
	ds_read_b128 v[212:215], v219 offset:7168
	s_waitcnt lgkmcnt(6)
	v_mfma_f32_32x32x16_bf16 v[148:163], v[180:183], v[184:187], v[148:163]
	ds_read_b64_tr_b16 v[180:181], v228 offset:34816
	ds_read_b64_tr_b16 v[182:183], v228 offset:35328
	ds_read_b64_tr_b16 v[184:185], v228 offset:35840
	ds_read_b64_tr_b16 v[186:187], v228 offset:36352
	s_waitcnt lgkmcnt(8)
	v_mfma_f32_32x32x16_bf16 v[132:147], v[188:191], v[192:195], v[132:147]
	ds_read_b64_tr_b16 v[188:189], v228 offset:38912
	ds_read_b64_tr_b16 v[190:191], v228 offset:39424
	ds_read_b64_tr_b16 v[192:193], v228 offset:39936
	ds_read_b64_tr_b16 v[194:195], v228 offset:40448
	s_waitcnt lgkmcnt(10)
	v_mfma_f32_32x32x16_bf16 v[132:147], v[200:203], v[204:207], v[132:147]
	ds_read_b64_tr_b16 v[200:201], v228 offset:43008
	ds_read_b64_tr_b16 v[202:203], v228 offset:43520
	ds_read_b64_tr_b16 v[204:205], v228 offset:44032
	ds_read_b64_tr_b16 v[206:207], v228 offset:44544
	s_waitcnt lgkmcnt(12)
	v_mfma_f32_32x32x16_bf16 v[132:147], v[208:211], v[212:215], v[132:147]
	ds_read_b64_tr_b16 v[208:209], v228 offset:47104
	ds_read_b64_tr_b16 v[210:211], v228 offset:47616
	v_exp_f32_e32 v148, v148
	v_exp_f32_e32 v149, v149
	v_exp_f32_e32 v150, v150
	v_exp_f32_e32 v151, v151
	v_exp_f32_e32 v152, v152
	v_exp_f32_e32 v153, v153
	v_exp_f32_e32 v154, v154
	v_exp_f32_e32 v155, v155
	v_exp_f32_e32 v156, v156
	v_exp_f32_e32 v157, v157
	v_exp_f32_e32 v158, v158
	v_exp_f32_e32 v159, v159
	v_exp_f32_e32 v160, v160
	v_exp_f32_e32 v161, v161
	v_exp_f32_e32 v162, v162
	v_exp_f32_e32 v163, v163
	v_add_f32_e32 v170, v170, v148
	v_add_f32_e32 v171, v171, v149
	v_cvt_pk_bf16_f32 v230, v148, v149
	v_add_f32_e32 v170, v170, v150
	v_add_f32_e32 v171, v171, v151
	v_cvt_pk_bf16_f32 v231, v150, v151
	v_add_f32_e32 v170, v170, v152
	v_add_f32_e32 v171, v171, v153
	v_cvt_pk_bf16_f32 v232, v152, v153
	v_add_f32_e32 v170, v170, v154
	v_add_f32_e32 v171, v171, v155
	v_cvt_pk_bf16_f32 v233, v154, v155
	v_add_f32_e32 v170, v170, v156
	v_add_f32_e32 v171, v171, v157
	v_cvt_pk_bf16_f32 v234, v156, v157
	v_add_f32_e32 v170, v170, v158
	v_add_f32_e32 v171, v171, v159
	v_cvt_pk_bf16_f32 v235, v158, v159
	v_add_f32_e32 v170, v170, v160
	v_add_f32_e32 v171, v171, v161
	v_cvt_pk_bf16_f32 v236, v160, v161
	v_add_f32_e32 v170, v170, v162
	v_add_f32_e32 v171, v171, v163
	v_cvt_pk_bf16_f32 v237, v162, v163
	s_waitcnt lgkmcnt(12)
	ds_read_b64_tr_b16 v[212:213], v228 offset:48128
	ds_read_b64_tr_b16 v[214:215], v228 offset:48640
	s_cmp_ge_i32 s13, s77
	s_cbranch_scc1 .Latt_b_flush
	s_cmp_eq_u32 s13, s78
	s_cbranch_scc1 .Latt_b_flush
	s_mov_b32 s101, 1
	s_branch .LBB0_981
.Latt_b_flush:
	s_setprio 2
	v_mfma_f32_32x32x16_bf16 v[100:115], v[180:183], v[230:233], v[100:115]
	v_exp_f32_e32 v132, v132
	v_exp_f32_e32 v133, v133
	s_waitcnt lgkmcnt(12)
	v_mfma_f32_32x32x16_bf16 v[100:115], v[184:187], v[234:237], v[100:115]
	v_exp_f32_e32 v134, v134
	v_exp_f32_e32 v135, v135
	v_add_f32_e32 v178, v178, v132
	v_add_f32_e32 v179, v179, v133
	v_cvt_pk_bf16_f32 v238, v132, v133
	s_waitcnt lgkmcnt(10)
	v_mfma_f32_32x32x16_bf16 v[68:83], v[188:191], v[230:233], v[68:83]
	v_exp_f32_e32 v136, v136
	v_exp_f32_e32 v137, v137
	v_add_f32_e32 v178, v178, v134
	v_add_f32_e32 v179, v179, v135
	v_cvt_pk_bf16_f32 v239, v134, v135
	s_waitcnt lgkmcnt(8)
	v_mfma_f32_32x32x16_bf16 v[68:83], v[192:195], v[234:237], v[68:83]
	v_exp_f32_e32 v138, v138
	v_exp_f32_e32 v139, v139
	v_add_f32_e32 v178, v178, v136
	v_add_f32_e32 v179, v179, v137
	v_cvt_pk_bf16_f32 v240, v136, v137
	s_waitcnt lgkmcnt(6)
	v_mfma_f32_32x32x16_bf16 v[34:49], v[200:203], v[230:233], v[34:49]
	v_exp_f32_e32 v140, v140
	v_exp_f32_e32 v141, v141
	v_add_f32_e32 v178, v178, v138
	v_add_f32_e32 v179, v179, v139
	v_cvt_pk_bf16_f32 v241, v138, v139
	s_waitcnt lgkmcnt(4)
	v_mfma_f32_32x32x16_bf16 v[34:49], v[204:207], v[234:237], v[34:49]
	v_exp_f32_e32 v142, v142
	v_exp_f32_e32 v143, v143
	v_add_f32_e32 v178, v178, v140
	v_add_f32_e32 v179, v179, v141
	v_cvt_pk_bf16_f32 v242, v140, v141
	s_waitcnt lgkmcnt(2)
	v_mfma_f32_32x32x16_bf16 v[18:33], v[208:211], v[230:233], v[18:33]
	v_exp_f32_e32 v144, v144
	v_exp_f32_e32 v145, v145
	v_add_f32_e32 v178, v178, v142
	v_add_f32_e32 v179, v179, v143
	v_cvt_pk_bf16_f32 v243, v142, v143
	s_waitcnt lgkmcnt(0)
	v_mfma_f32_32x32x16_bf16 v[18:33], v[212:215], v[234:237], v[18:33]
	v_exp_f32_e32 v146, v146
	v_exp_f32_e32 v147, v147
	v_add_f32_e32 v178, v178, v144
	v_add_f32_e32 v179, v179, v145
	v_cvt_pk_bf16_f32 v244, v144, v145
	s_nop 0
	v_add_f32_e32 v178, v178, v146
	v_add_f32_e32 v179, v179, v147
	v_cvt_pk_bf16_f32 v245, v146, v147
	v_mfma_f32_32x32x16_bf16 v[116:131], v[180:183], v[238:241], v[116:131]
	v_mfma_f32_32x32x16_bf16 v[116:131], v[184:187], v[242:245], v[116:131]
	v_mfma_f32_32x32x16_bf16 v[84:99], v[188:191], v[238:241], v[84:99]
	v_mfma_f32_32x32x16_bf16 v[84:99], v[192:195], v[242:245], v[84:99]
	v_mfma_f32_32x32x16_bf16 v[50:65], v[200:203], v[238:241], v[50:65]
	v_mfma_f32_32x32x16_bf16 v[50:65], v[204:207], v[242:245], v[50:65]
	v_mfma_f32_32x32x16_bf16 v[2:17], v[208:211], v[238:241], v[2:17]
	v_mfma_f32_32x32x16_bf16 v[2:17], v[212:215], v[242:245], v[2:17]
	s_setprio 0
	s_branch .LBB0_981
